# P5 SwiGLU epilogue: silu(rs*g)*(rs*u) evaluated as (g*u)*rs^2/(1+exp2(-log2e*rs*g)) -- one multiply fewer per output
# speedup vs baseline: 1.0072x; 1.0072x over previous
; __device__ __forceinline__ unsigned cvt_pk_bf16(float lo, float hi) { unsigned r; asm volatile("v_cvt_pk_bf16_f32 %0, %1, %2" : "=v"(r) : "v"(lo), "v"(hi)); return r; }
;     __device__ __forceinline__ void operator()(const f32x4 (&acc)[2][2][4][2], const Unit& u, int wr, int wc, int fr, int fq) const {
;         const int row0 = u.pm * BM + wr * 64 + fr, col0 = u.pn * HALF + wc * 32 + 8 * fq;
;         float rsv[2][4];
; #pragma unroll
;         for (int ai = 0; ai < 2; ++ai)
; #pragma unroll
;             for (int m = 0; m < 4; ++m) rsv[ai][m] = ss[row0 + ai * HALF + m * 16];
;         asm volatile("" ::: "memory");
; #pragma unroll
;         for (int ai = 0; ai < 2; ++ai)
; #pragma unroll
;             for (int m = 0; m < 4; ++m) { const int row = row0 + ai * HALF + m * 16; const float rs = __builtin_amdgcn_rsqf(rsv[ai][m] * inv_n + eps);
;                 float a[8];
; #pragma unroll
;                 for (int n = 0; n < 2; ++n)
; #pragma unroll
;                     for (int i = 0; i < 4; ++i) { const float g = acc[ai][0][m][n][i] * rs, up = acc[ai][1][m][n][i] * rs;
;                         a[n * 4 + i] = g * __builtin_amdgcn_rcpf(1.0f + __builtin_amdgcn_exp2f(-1.4426950408889634f * g)) * up; }
;                 u32x4 w; w.x = cvt_pk_bf16(a[0], a[1]); w.y = cvt_pk_bf16(a[2], a[3]); w.z = cvt_pk_bf16(a[4], a[5]); w.w = cvt_pk_bf16(a[6], a[7]);
;                 *(u32x4*)(O + (size_t)row * ldc + col0) = w; }
;     }
.Lp5_kdone:
	s_waitcnt lgkmcnt(0)
	s_nop 7
	s_nop 7
	v_mov_b32_e32 v134, v254
	v_mov_b32_e32 v135, v255
	v_mov_b32_e32 v136, v186
	v_mov_b32_e32 v137, v187
	v_and_b32_e32 v254, 63, v185
	v_and_b32_e32 v255, 15, v254
	v_lshrrev_b32_e32 v186, 4, v254
	s_lshl_b32 s40, s37, 6
	v_add_u32_e32 v255, s40, v255
	v_lshlrev_b32_e32 v128, 2, v255
	v_mul_u32_u24_e32 v129, 0x2c00, v255
	s_lshl_b32 s41, s38, 6
	v_lshl_add_u32 v129, v186, 4, v129
	v_add_u32_e32 v129, s41, v129
	v_mov_b32_e32 v130, 0x358637bd
	s_lshl_b32 s40, s17, 10
	s_add_u32 s48, s76, s40
	s_addc_u32 s49, s77, 0
	s_mul_i32 s40, s17, 0x2c0000
	s_lshl_b32 s41, s18, 8
	s_add_u32 s40, s40, s41
	s_add_u32 s50, s76, 0xa800000
	s_addc_u32 s51, s77, 0
	s_add_u32 s50, s50, s40
	s_addc_u32 s51, s51, 0
	global_load_dword v138, v128, s[48:49] offset:512
	global_load_dword v139, v128, s[48:49] offset:576
	global_load_dword v140, v128, s[48:49] offset:640
	global_load_dword v141, v128, s[48:49] offset:704
	v_fmamk_f32 v131, v134, 0x3a000000, v130
	v_add_u32_e32 v132, 0x0, v129
	v_rsq_f32_e32 v131, v131
	s_nop 0
	v_mul_f32_e32 v133, 0xbfb8aa3b, v131
	v_mul_f32_e32 v131, v131, v131
	v_mul_f32_e32 v144, v133, v0
	v_mul_f32_e32 v145, v133, v1
	v_mul_f32_e32 v146, v133, v2
	v_mul_f32_e32 v147, v133, v3
	v_mul_f32_e32 v148, v133, v4
	v_mul_f32_e32 v149, v133, v5
	v_mul_f32_e32 v150, v133, v6
	v_mul_f32_e32 v151, v133, v7
	v_exp_f32_e32 v144, v144
	v_exp_f32_e32 v145, v145
	v_exp_f32_e32 v146, v146
	v_exp_f32_e32 v147, v147
	v_exp_f32_e32 v148, v148
	v_exp_f32_e32 v149, v149
	v_exp_f32_e32 v150, v150
	v_exp_f32_e32 v151, v151
	v_mul_f32_e32 v0, v0, v32
	v_mul_f32_e32 v1, v1, v33
	v_mul_f32_e32 v2, v2, v34
	v_mul_f32_e32 v3, v3, v35
	v_mul_f32_e32 v4, v4, v36
	v_mul_f32_e32 v5, v5, v37
	v_mul_f32_e32 v6, v6, v38
	v_mul_f32_e32 v7, v7, v39
	v_add_f32_e32 v144, 1.0, v144
	v_add_f32_e32 v145, 1.0, v145
	v_add_f32_e32 v146, 1.0, v146
	v_add_f32_e32 v147, 1.0, v147
	v_add_f32_e32 v148, 1.0, v148
	v_add_f32_e32 v149, 1.0, v149
	v_add_f32_e32 v150, 1.0, v150
	v_add_f32_e32 v151, 1.0, v151
	v_rcp_f32_e32 v144, v144
	v_rcp_f32_e32 v145, v145
	v_rcp_f32_e32 v146, v146
	v_rcp_f32_e32 v147, v147
	v_rcp_f32_e32 v148, v148
	v_rcp_f32_e32 v149, v149
	v_rcp_f32_e32 v150, v150
	v_rcp_f32_e32 v151, v151
	v_mul_f32_e32 v0, v0, v131
	v_mul_f32_e32 v1, v1, v131
	v_mul_f32_e32 v2, v2, v131
	v_mul_f32_e32 v3, v3, v131
	v_mul_f32_e32 v4, v4, v131
	v_mul_f32_e32 v5, v5, v131
	v_mul_f32_e32 v6, v6, v131
	v_mul_f32_e32 v7, v7, v131
	v_mul_f32_e32 v0, v0, v144
	v_mul_f32_e32 v1, v1, v145
	v_mul_f32_e32 v2, v2, v146
	v_mul_f32_e32 v3, v3, v147
	v_mul_f32_e32 v4, v4, v148
	v_mul_f32_e32 v5, v5, v149
	v_mul_f32_e32 v6, v6, v150
	v_mul_f32_e32 v7, v7, v151
	v_cvt_pk_bf16_f32 v152, v0, v1
	v_cvt_pk_bf16_f32 v153, v2, v3
	v_cvt_pk_bf16_f32 v154, v4, v5
	v_cvt_pk_bf16_f32 v155, v6, v7
	s_nop 1
	global_store_dwordx4 v132, v[152:155], s[50:51]
	s_nop 1
	v_fmamk_f32 v131, v135, 0x3a000000, v130
	v_add_u32_e32 v132, 0x2c000, v129
	v_rsq_f32_e32 v131, v131
	s_nop 0
	v_mul_f32_e32 v133, 0xbfb8aa3b, v131
	v_mul_f32_e32 v131, v131, v131
	v_mul_f32_e32 v144, v133, v8
	v_mul_f32_e32 v145, v133, v9
	v_mul_f32_e32 v146, v133, v10
	v_mul_f32_e32 v147, v133, v11
	v_mul_f32_e32 v148, v133, v12
	v_mul_f32_e32 v149, v133, v13
	v_mul_f32_e32 v150, v133, v14
	v_mul_f32_e32 v151, v133, v15
	v_exp_f32_e32 v144, v144
	v_exp_f32_e32 v145, v145
	v_exp_f32_e32 v146, v146
	v_exp_f32_e32 v147, v147
	v_exp_f32_e32 v148, v148
	v_exp_f32_e32 v149, v149
	v_exp_f32_e32 v150, v150
	v_exp_f32_e32 v151, v151
	v_mul_f32_e32 v8, v8, v40
	v_mul_f32_e32 v9, v9, v41
	v_mul_f32_e32 v10, v10, v42
	v_mul_f32_e32 v11, v11, v43
	v_mul_f32_e32 v12, v12, v44
	v_mul_f32_e32 v13, v13, v45
	v_mul_f32_e32 v14, v14, v46
	v_mul_f32_e32 v15, v15, v47
	v_add_f32_e32 v144, 1.0, v144
	v_add_f32_e32 v145, 1.0, v145
	v_add_f32_e32 v146, 1.0, v146
	v_add_f32_e32 v147, 1.0, v147
	v_add_f32_e32 v148, 1.0, v148
	v_add_f32_e32 v149, 1.0, v149
	v_add_f32_e32 v150, 1.0, v150
	v_add_f32_e32 v151, 1.0, v151
	v_rcp_f32_e32 v144, v144
	v_rcp_f32_e32 v145, v145
	v_rcp_f32_e32 v146, v146
	v_rcp_f32_e32 v147, v147
	v_rcp_f32_e32 v148, v148
	v_rcp_f32_e32 v149, v149
	v_rcp_f32_e32 v150, v150
	v_rcp_f32_e32 v151, v151
	v_mul_f32_e32 v8, v8, v131
	v_mul_f32_e32 v9, v9, v131
	v_mul_f32_e32 v10, v10, v131
	v_mul_f32_e32 v11, v11, v131
	v_mul_f32_e32 v12, v12, v131
	v_mul_f32_e32 v13, v13, v131
	v_mul_f32_e32 v14, v14, v131
	v_mul_f32_e32 v15, v15, v131
	v_mul_f32_e32 v8, v8, v144
	v_mul_f32_e32 v9, v9, v145
	v_mul_f32_e32 v10, v10, v146
	v_mul_f32_e32 v11, v11, v147
	v_mul_f32_e32 v12, v12, v148
	v_mul_f32_e32 v13, v13, v149
	v_mul_f32_e32 v14, v14, v150
	v_mul_f32_e32 v15, v15, v151
	v_cvt_pk_bf16_f32 v152, v8, v9
	v_cvt_pk_bf16_f32 v153, v10, v11
	v_cvt_pk_bf16_f32 v154, v12, v13
	v_cvt_pk_bf16_f32 v155, v14, v15
	s_nop 1
	global_store_dwordx4 v132, v[152:155], s[50:51]
	s_nop 1
	v_fmamk_f32 v131, v136, 0x3a000000, v130
	v_add_u32_e32 v132, 0x58000, v129
	v_rsq_f32_e32 v131, v131
	s_nop 0
	v_mul_f32_e32 v133, 0xbfb8aa3b, v131
	v_mul_f32_e32 v131, v131, v131
	v_mul_f32_e32 v144, v133, v16
	v_mul_f32_e32 v145, v133, v17
	v_mul_f32_e32 v146, v133, v18
	v_mul_f32_e32 v147, v133, v19
	v_mul_f32_e32 v148, v133, v20
	v_mul_f32_e32 v149, v133, v21
	v_mul_f32_e32 v150, v133, v22
	v_mul_f32_e32 v151, v133, v23
	v_exp_f32_e32 v144, v144
	v_exp_f32_e32 v145, v145
	v_exp_f32_e32 v146, v146
	v_exp_f32_e32 v147, v147
	v_exp_f32_e32 v148, v148
	v_exp_f32_e32 v149, v149
	v_exp_f32_e32 v150, v150
	v_exp_f32_e32 v151, v151
	v_mul_f32_e32 v16, v16, v48
	v_mul_f32_e32 v17, v17, v49
	v_mul_f32_e32 v18, v18, v50
	v_mul_f32_e32 v19, v19, v51
; __device__ __forceinline__ unsigned cvt_pk_bf16(float lo, float hi) { unsigned r; asm volatile("v_cvt_pk_bf16_f32 %0, %1, %2" : "=v"(r) : "v"(lo), "v"(hi)); return r; }
;     __device__ __forceinline__ void operator()(const f32x4 (&acc)[2][2][4][2], const Unit& u, int wr, int wc, int fr, int fq) const {
;     ...
;         for (int ai = 0; ai < 2; ++ai)
; #pragma unroll
;             for (int m = 0; m < 4; ++m) { const int row = row0 + ai * HALF + m * 16; const float rs = __builtin_amdgcn_rsqf(rsv[ai][m] * inv_n + eps);
;                 float a[8];
; #pragma unroll
;                 for (int n = 0; n < 2; ++n)
; #pragma unroll
;                     for (int i = 0; i < 4; ++i) { const float g = acc[ai][0][m][n][i] * rs, up = acc[ai][1][m][n][i] * rs;
;                         a[n * 4 + i] = g * __builtin_amdgcn_rcpf(1.0f + __builtin_amdgcn_exp2f(-1.4426950408889634f * g)) * up; }
;                 u32x4 w; w.x = cvt_pk_bf16(a[0], a[1]); w.y = cvt_pk_bf16(a[2], a[3]); w.z = cvt_pk_bf16(a[4], a[5]); w.w = cvt_pk_bf16(a[6], a[7]);
;                 *(u32x4*)(O + (size_t)row * ldc + col0) = w; }
	v_mul_f32_e32 v20, v20, v52
	v_mul_f32_e32 v21, v21, v53
	v_mul_f32_e32 v22, v22, v54
	v_mul_f32_e32 v23, v23, v55
	v_add_f32_e32 v144, 1.0, v144
	v_add_f32_e32 v145, 1.0, v145
	v_add_f32_e32 v146, 1.0, v146
	v_add_f32_e32 v147, 1.0, v147
	v_add_f32_e32 v148, 1.0, v148
	v_add_f32_e32 v149, 1.0, v149
	v_add_f32_e32 v150, 1.0, v150
	v_add_f32_e32 v151, 1.0, v151
	v_rcp_f32_e32 v144, v144
	v_rcp_f32_e32 v145, v145
	v_rcp_f32_e32 v146, v146
	v_rcp_f32_e32 v147, v147
	v_rcp_f32_e32 v148, v148
	v_rcp_f32_e32 v149, v149
	v_rcp_f32_e32 v150, v150
	v_rcp_f32_e32 v151, v151
	v_mul_f32_e32 v16, v16, v131
	v_mul_f32_e32 v17, v17, v131
	v_mul_f32_e32 v18, v18, v131
	v_mul_f32_e32 v19, v19, v131
	v_mul_f32_e32 v20, v20, v131
	v_mul_f32_e32 v21, v21, v131
	v_mul_f32_e32 v22, v22, v131
	v_mul_f32_e32 v23, v23, v131
	v_mul_f32_e32 v16, v16, v144
	v_mul_f32_e32 v17, v17, v145
	v_mul_f32_e32 v18, v18, v146
	v_mul_f32_e32 v19, v19, v147
	v_mul_f32_e32 v20, v20, v148
	v_mul_f32_e32 v21, v21, v149
	v_mul_f32_e32 v22, v22, v150
	v_mul_f32_e32 v23, v23, v151
	v_cvt_pk_bf16_f32 v152, v16, v17
	v_cvt_pk_bf16_f32 v153, v18, v19
	v_cvt_pk_bf16_f32 v154, v20, v21
	v_cvt_pk_bf16_f32 v155, v22, v23
	s_nop 1
	global_store_dwordx4 v132, v[152:155], s[50:51]
	s_nop 1
	v_fmamk_f32 v131, v137, 0x3a000000, v130
	v_add_u32_e32 v132, 0x84000, v129
	v_rsq_f32_e32 v131, v131
	s_nop 0
	v_mul_f32_e32 v133, 0xbfb8aa3b, v131
	v_mul_f32_e32 v131, v131, v131
	v_mul_f32_e32 v144, v133, v24
	v_mul_f32_e32 v145, v133, v25
	v_mul_f32_e32 v146, v133, v26
	v_mul_f32_e32 v147, v133, v27
	v_mul_f32_e32 v148, v133, v28
	v_mul_f32_e32 v149, v133, v29
	v_mul_f32_e32 v150, v133, v30
	v_mul_f32_e32 v151, v133, v31
	v_exp_f32_e32 v144, v144
	v_exp_f32_e32 v145, v145
	v_exp_f32_e32 v146, v146
	v_exp_f32_e32 v147, v147
	v_exp_f32_e32 v148, v148
	v_exp_f32_e32 v149, v149
	v_exp_f32_e32 v150, v150
	v_exp_f32_e32 v151, v151
	v_mul_f32_e32 v24, v24, v56
	v_mul_f32_e32 v25, v25, v57
	v_mul_f32_e32 v26, v26, v58
	v_mul_f32_e32 v27, v27, v59
	v_mul_f32_e32 v28, v28, v60
	v_mul_f32_e32 v29, v29, v61
	v_mul_f32_e32 v30, v30, v62
	v_mul_f32_e32 v31, v31, v63
	v_add_f32_e32 v144, 1.0, v144
	v_add_f32_e32 v145, 1.0, v145
	v_add_f32_e32 v146, 1.0, v146
	v_add_f32_e32 v147, 1.0, v147
	v_add_f32_e32 v148, 1.0, v148
	v_add_f32_e32 v149, 1.0, v149
	v_add_f32_e32 v150, 1.0, v150
	v_add_f32_e32 v151, 1.0, v151
	v_rcp_f32_e32 v144, v144
	v_rcp_f32_e32 v145, v145
	v_rcp_f32_e32 v146, v146
	v_rcp_f32_e32 v147, v147
	v_rcp_f32_e32 v148, v148
	v_rcp_f32_e32 v149, v149
	v_rcp_f32_e32 v150, v150
	v_rcp_f32_e32 v151, v151
	v_mul_f32_e32 v24, v24, v131
	v_mul_f32_e32 v25, v25, v131
	v_mul_f32_e32 v26, v26, v131
	v_mul_f32_e32 v27, v27, v131
	v_mul_f32_e32 v28, v28, v131
	v_mul_f32_e32 v29, v29, v131
	v_mul_f32_e32 v30, v30, v131
	v_mul_f32_e32 v31, v31, v131
	v_mul_f32_e32 v24, v24, v144
	v_mul_f32_e32 v25, v25, v145
	v_mul_f32_e32 v26, v26, v146
	v_mul_f32_e32 v27, v27, v147
	v_mul_f32_e32 v28, v28, v148
	v_mul_f32_e32 v29, v29, v149
	v_mul_f32_e32 v30, v30, v150
	v_mul_f32_e32 v31, v31, v151
	v_cvt_pk_bf16_f32 v152, v24, v25
	v_cvt_pk_bf16_f32 v153, v26, v27
	v_cvt_pk_bf16_f32 v154, v28, v29
	v_cvt_pk_bf16_f32 v155, v30, v31
	s_nop 1
	global_store_dwordx4 v132, v[152:155], s[50:51]
	s_nop 1
	s_waitcnt vmcnt(4)
	v_fmamk_f32 v131, v138, 0x3a000000, v130
	v_add_u32_e32 v132, 0x160000, v129
	v_rsq_f32_e32 v131, v131
	s_nop 0
	v_mul_f32_e32 v133, 0xbfb8aa3b, v131
	v_mul_f32_e32 v131, v131, v131
	v_mul_f32_e32 v144, v133, v64
	v_mul_f32_e32 v145, v133, v65
	v_mul_f32_e32 v146, v133, v66
	v_mul_f32_e32 v147, v133, v67
	v_mul_f32_e32 v148, v133, v68
	v_mul_f32_e32 v149, v133, v69
	v_mul_f32_e32 v150, v133, v70
	v_mul_f32_e32 v151, v133, v71
	v_exp_f32_e32 v144, v144
	v_exp_f32_e32 v145, v145
	v_exp_f32_e32 v146, v146
	v_exp_f32_e32 v147, v147
	v_exp_f32_e32 v148, v148
	v_exp_f32_e32 v149, v149
	v_exp_f32_e32 v150, v150
	v_exp_f32_e32 v151, v151
	v_mul_f32_e32 v64, v64, v96
	v_mul_f32_e32 v65, v65, v97
	v_mul_f32_e32 v66, v66, v98
	v_mul_f32_e32 v67, v67, v99
	v_mul_f32_e32 v68, v68, v100
	v_mul_f32_e32 v69, v69, v101
	v_mul_f32_e32 v70, v70, v102
	v_mul_f32_e32 v71, v71, v103
	v_add_f32_e32 v144, 1.0, v144
	v_add_f32_e32 v145, 1.0, v145
	v_add_f32_e32 v146, 1.0, v146
	v_add_f32_e32 v147, 1.0, v147
	v_add_f32_e32 v148, 1.0, v148
	v_add_f32_e32 v149, 1.0, v149
	v_add_f32_e32 v150, 1.0, v150
	v_add_f32_e32 v151, 1.0, v151
	v_rcp_f32_e32 v144, v144
	v_rcp_f32_e32 v145, v145
	v_rcp_f32_e32 v146, v146
	v_rcp_f32_e32 v147, v147
	v_rcp_f32_e32 v148, v148
	v_rcp_f32_e32 v149, v149
	v_rcp_f32_e32 v150, v150
	v_rcp_f32_e32 v151, v151
	v_mul_f32_e32 v64, v64, v131
	v_mul_f32_e32 v65, v65, v131
	v_mul_f32_e32 v66, v66, v131
	v_mul_f32_e32 v67, v67, v131
	v_mul_f32_e32 v68, v68, v131
	v_mul_f32_e32 v69, v69, v131
	v_mul_f32_e32 v70, v70, v131
	v_mul_f32_e32 v71, v71, v131
	v_mul_f32_e32 v64, v64, v144
	v_mul_f32_e32 v65, v65, v145
	v_mul_f32_e32 v66, v66, v146
	v_mul_f32_e32 v67, v67, v147
	v_mul_f32_e32 v68, v68, v148
	v_mul_f32_e32 v69, v69, v149
	v_mul_f32_e32 v70, v70, v150
	v_mul_f32_e32 v71, v71, v151
	v_cvt_pk_bf16_f32 v152, v64, v65
	v_cvt_pk_bf16_f32 v153, v66, v67
	v_cvt_pk_bf16_f32 v154, v68, v69
	v_cvt_pk_bf16_f32 v155, v70, v71
	s_nop 1
	global_store_dwordx4 v132, v[152:155], s[50:51]
	s_nop 1
	v_fmamk_f32 v131, v139, 0x3a000000, v130
	v_add_u32_e32 v132, 0x18c000, v129
	v_rsq_f32_e32 v131, v131
	s_nop 0
	v_mul_f32_e32 v133, 0xbfb8aa3b, v131
	v_mul_f32_e32 v131, v131, v131
	v_mul_f32_e32 v144, v133, v72
	v_mul_f32_e32 v145, v133, v73
	v_mul_f32_e32 v146, v133, v74
	v_mul_f32_e32 v147, v133, v75
	v_mul_f32_e32 v148, v133, v76
; __device__ __forceinline__ unsigned cvt_pk_bf16(float lo, float hi) { unsigned r; asm volatile("v_cvt_pk_bf16_f32 %0, %1, %2" : "=v"(r) : "v"(lo), "v"(hi)); return r; }
;     __device__ __forceinline__ void operator()(const f32x4 (&acc)[2][2][4][2], const Unit& u, int wr, int wc, int fr, int fq) const {
;     ...
;         for (int ai = 0; ai < 2; ++ai)
; #pragma unroll
;             for (int m = 0; m < 4; ++m) { const int row = row0 + ai * HALF + m * 16; const float rs = __builtin_amdgcn_rsqf(rsv[ai][m] * inv_n + eps);
;                 float a[8];
; #pragma unroll
;                 for (int n = 0; n < 2; ++n)
; #pragma unroll
;                     for (int i = 0; i < 4; ++i) { const float g = acc[ai][0][m][n][i] * rs, up = acc[ai][1][m][n][i] * rs;
;                         a[n * 4 + i] = g * __builtin_amdgcn_rcpf(1.0f + __builtin_amdgcn_exp2f(-1.4426950408889634f * g)) * up; }
;                 u32x4 w; w.x = cvt_pk_bf16(a[0], a[1]); w.y = cvt_pk_bf16(a[2], a[3]); w.z = cvt_pk_bf16(a[4], a[5]); w.w = cvt_pk_bf16(a[6], a[7]);
;                 *(u32x4*)(O + (size_t)row * ldc + col0) = w; }
; template <class Epi, class Sched, bool ALIGN_EPI = false, bool SP2 = false>
; __device__ __forceinline__ void gemm_phase(PG8_LAS unsigned char* lds, const Gemm g, const Sched& S, const Epi& E) {
;     ...
;         if (!has_next) break;
; #pragma unroll
;         for (int a = 0; a < 2; ++a)
; #pragma unroll
;             for (int b = 0; b < 2; ++b)
; #pragma unroll
;                 for (int m = 0; m < 4; ++m)
; #pragma unroll
;                     for (int n = 0; n < 2; ++n) acc[a][b][m][n] = (f32x4){0.f, 0.f, 0.f, 0.f};
;         cur = nxt; cA = nA; cB = nB; ++ui;
	v_mul_f32_e32 v149, v133, v77
	v_mul_f32_e32 v150, v133, v78
	v_mul_f32_e32 v151, v133, v79
	v_exp_f32_e32 v144, v144
	v_exp_f32_e32 v145, v145
	v_exp_f32_e32 v146, v146
	v_exp_f32_e32 v147, v147
	v_exp_f32_e32 v148, v148
	v_exp_f32_e32 v149, v149
	v_exp_f32_e32 v150, v150
	v_exp_f32_e32 v151, v151
	v_mul_f32_e32 v72, v72, v104
	v_mul_f32_e32 v73, v73, v105
	v_mul_f32_e32 v74, v74, v106
	v_mul_f32_e32 v75, v75, v107
	v_mul_f32_e32 v76, v76, v108
	v_mul_f32_e32 v77, v77, v109
	v_mul_f32_e32 v78, v78, v110
	v_mul_f32_e32 v79, v79, v111
	v_add_f32_e32 v144, 1.0, v144
	v_add_f32_e32 v145, 1.0, v145
	v_add_f32_e32 v146, 1.0, v146
	v_add_f32_e32 v147, 1.0, v147
	v_add_f32_e32 v148, 1.0, v148
	v_add_f32_e32 v149, 1.0, v149
	v_add_f32_e32 v150, 1.0, v150
	v_add_f32_e32 v151, 1.0, v151
	v_rcp_f32_e32 v144, v144
	v_rcp_f32_e32 v145, v145
	v_rcp_f32_e32 v146, v146
	v_rcp_f32_e32 v147, v147
	v_rcp_f32_e32 v148, v148
	v_rcp_f32_e32 v149, v149
	v_rcp_f32_e32 v150, v150
	v_rcp_f32_e32 v151, v151
	v_mul_f32_e32 v72, v72, v131
	v_mul_f32_e32 v73, v73, v131
	v_mul_f32_e32 v74, v74, v131
	v_mul_f32_e32 v75, v75, v131
	v_mul_f32_e32 v76, v76, v131
	v_mul_f32_e32 v77, v77, v131
	v_mul_f32_e32 v78, v78, v131
	v_mul_f32_e32 v79, v79, v131
	v_mul_f32_e32 v72, v72, v144
	v_mul_f32_e32 v73, v73, v145
	v_mul_f32_e32 v74, v74, v146
	v_mul_f32_e32 v75, v75, v147
	v_mul_f32_e32 v76, v76, v148
	v_mul_f32_e32 v77, v77, v149
	v_mul_f32_e32 v78, v78, v150
	v_mul_f32_e32 v79, v79, v151
	v_cvt_pk_bf16_f32 v152, v72, v73
	v_cvt_pk_bf16_f32 v153, v74, v75
	v_cvt_pk_bf16_f32 v154, v76, v77
	v_cvt_pk_bf16_f32 v155, v78, v79
	s_nop 1
	global_store_dwordx4 v132, v[152:155], s[50:51]
	s_nop 1
	v_fmamk_f32 v131, v140, 0x3a000000, v130
	v_add_u32_e32 v132, 0x1b8000, v129
	v_rsq_f32_e32 v131, v131
	s_nop 0
	v_mul_f32_e32 v133, 0xbfb8aa3b, v131
	v_mul_f32_e32 v131, v131, v131
	v_mul_f32_e32 v144, v133, v80
	v_mul_f32_e32 v145, v133, v81
	v_mul_f32_e32 v146, v133, v82
	v_mul_f32_e32 v147, v133, v83
	v_mul_f32_e32 v148, v133, v84
	v_mul_f32_e32 v149, v133, v85
	v_mul_f32_e32 v150, v133, v86
	v_mul_f32_e32 v151, v133, v87
	v_exp_f32_e32 v144, v144
	v_exp_f32_e32 v145, v145
	v_exp_f32_e32 v146, v146
	v_exp_f32_e32 v147, v147
	v_exp_f32_e32 v148, v148
	v_exp_f32_e32 v149, v149
	v_exp_f32_e32 v150, v150
	v_exp_f32_e32 v151, v151
	v_mul_f32_e32 v80, v80, v112
	v_mul_f32_e32 v81, v81, v113
	v_mul_f32_e32 v82, v82, v114
	v_mul_f32_e32 v83, v83, v115
	v_mul_f32_e32 v84, v84, v116
	v_mul_f32_e32 v85, v85, v117
	v_mul_f32_e32 v86, v86, v118
	v_mul_f32_e32 v87, v87, v119
	v_add_f32_e32 v144, 1.0, v144
	v_add_f32_e32 v145, 1.0, v145
	v_add_f32_e32 v146, 1.0, v146
	v_add_f32_e32 v147, 1.0, v147
	v_add_f32_e32 v148, 1.0, v148
	v_add_f32_e32 v149, 1.0, v149
	v_add_f32_e32 v150, 1.0, v150
	v_add_f32_e32 v151, 1.0, v151
	v_rcp_f32_e32 v144, v144
	v_rcp_f32_e32 v145, v145
	v_rcp_f32_e32 v146, v146
	v_rcp_f32_e32 v147, v147
	v_rcp_f32_e32 v148, v148
	v_rcp_f32_e32 v149, v149
	v_rcp_f32_e32 v150, v150
	v_rcp_f32_e32 v151, v151
	v_mul_f32_e32 v80, v80, v131
	v_mul_f32_e32 v81, v81, v131
	v_mul_f32_e32 v82, v82, v131
	v_mul_f32_e32 v83, v83, v131
	v_mul_f32_e32 v84, v84, v131
	v_mul_f32_e32 v85, v85, v131
	v_mul_f32_e32 v86, v86, v131
	v_mul_f32_e32 v87, v87, v131
	v_mul_f32_e32 v80, v80, v144
	v_mul_f32_e32 v81, v81, v145
	v_mul_f32_e32 v82, v82, v146
	v_mul_f32_e32 v83, v83, v147
	v_mul_f32_e32 v84, v84, v148
	v_mul_f32_e32 v85, v85, v149
	v_mul_f32_e32 v86, v86, v150
	v_mul_f32_e32 v87, v87, v151
	v_cvt_pk_bf16_f32 v152, v80, v81
	v_cvt_pk_bf16_f32 v153, v82, v83
	v_cvt_pk_bf16_f32 v154, v84, v85
	v_cvt_pk_bf16_f32 v155, v86, v87
	s_nop 1
	global_store_dwordx4 v132, v[152:155], s[50:51]
	s_nop 1
	v_fmamk_f32 v131, v141, 0x3a000000, v130
	v_add_u32_e32 v132, 0x1e4000, v129
	v_rsq_f32_e32 v131, v131
	s_nop 0
	v_mul_f32_e32 v133, 0xbfb8aa3b, v131
	v_mul_f32_e32 v131, v131, v131
	v_mul_f32_e32 v144, v133, v88
	v_mul_f32_e32 v145, v133, v89
	v_mul_f32_e32 v146, v133, v90
	v_mul_f32_e32 v147, v133, v91
	v_mul_f32_e32 v148, v133, v92
	v_mul_f32_e32 v149, v133, v93
	v_mul_f32_e32 v150, v133, v94
	v_mul_f32_e32 v151, v133, v95
	v_exp_f32_e32 v144, v144
	v_exp_f32_e32 v145, v145
	v_exp_f32_e32 v146, v146
	v_exp_f32_e32 v147, v147
	v_exp_f32_e32 v148, v148
	v_exp_f32_e32 v149, v149
	v_exp_f32_e32 v150, v150
	v_exp_f32_e32 v151, v151
	v_mul_f32_e32 v88, v88, v120
	v_mul_f32_e32 v89, v89, v121
	v_mul_f32_e32 v90, v90, v122
	v_mul_f32_e32 v91, v91, v123
	v_mul_f32_e32 v92, v92, v124
	v_mul_f32_e32 v93, v93, v125
	v_mul_f32_e32 v94, v94, v126
	v_mul_f32_e32 v95, v95, v127
	v_add_f32_e32 v144, 1.0, v144
	v_add_f32_e32 v145, 1.0, v145
	v_add_f32_e32 v146, 1.0, v146
	v_add_f32_e32 v147, 1.0, v147
	v_add_f32_e32 v148, 1.0, v148
	v_add_f32_e32 v149, 1.0, v149
	v_add_f32_e32 v150, 1.0, v150
	v_add_f32_e32 v151, 1.0, v151
	v_rcp_f32_e32 v144, v144
	v_rcp_f32_e32 v145, v145
	v_rcp_f32_e32 v146, v146
	v_rcp_f32_e32 v147, v147
	v_rcp_f32_e32 v148, v148
	v_rcp_f32_e32 v149, v149
	v_rcp_f32_e32 v150, v150
	v_rcp_f32_e32 v151, v151
	v_mul_f32_e32 v88, v88, v131
	v_mul_f32_e32 v89, v89, v131
	v_mul_f32_e32 v90, v90, v131
	v_mul_f32_e32 v91, v91, v131
	v_mul_f32_e32 v92, v92, v131
	v_mul_f32_e32 v93, v93, v131
	v_mul_f32_e32 v94, v94, v131
	v_mul_f32_e32 v95, v95, v131
	v_mul_f32_e32 v88, v88, v144
	v_mul_f32_e32 v89, v89, v145
	v_mul_f32_e32 v90, v90, v146
	v_mul_f32_e32 v91, v91, v147
	v_mul_f32_e32 v92, v92, v148
	v_mul_f32_e32 v93, v93, v149
	v_mul_f32_e32 v94, v94, v150
	v_mul_f32_e32 v95, v95, v151
	v_cvt_pk_bf16_f32 v152, v88, v89
	v_cvt_pk_bf16_f32 v153, v90, v91
	v_cvt_pk_bf16_f32 v154, v92, v93
	v_cvt_pk_bf16_f32 v155, v94, v95
	s_nop 1
	global_store_dwordx4 v132, v[152:155], s[50:51]
	s_nop 1
	s_cmp_eq_u32 s19, 0
	s_cbranch_scc1 .Lp5_done
	s_mov_b32 s17, s20
	s_mov_b32 s18, s21
	s_mov_b64 s[22:23], s[26:27]
	s_mov_b64 s[24:25], s[28:29]
	s_add_u32 s16, s16, 1
	s_branch .Lp5_unit

;     __device__ __forceinline__ void operator()(const f32x4 (&acc)[2][2][4][2], const Unit& u, int wr, int wc, int fr, int fq) const {
;         const int col0 = u.pn * BM + wc * 32 + 8 * fq;
;         if constexpr (BASE_BF16) {
;             u32x4 raw[2][4][2];
; #pragma unroll
;             for (int ai = 0; ai < 2; ++ai)
; #pragma unroll
;                 for (int m = 0; m < 4; ++m) { const int row = u.pm * BM + ai * HALF + wr * 64 + m * 16 + fr; const size_t off = (size_t)row * ldc + col0;
; #pragma unroll
;                     for (int bj = 0; bj < 2; ++bj) raw[ai][m][bj] = *(const u32x4*)((const bf16_t*)base + off + bj * HALF); }
;             asm volatile("" ::: "memory");
; #pragma unroll
;             for (int ai = 0; ai < 2; ++ai)
; #pragma unroll
;                 for (int m = 0; m < 4; ++m) { const int row = u.pm * BM + ai * HALF + wr * 64 + m * 16 + fr; const size_t off = (size_t)row * ldc + col0; float s = 0.f;
; #pragma unroll
;                     for (int bj = 0; bj < 2; ++bj) { const u32x4 r = raw[ai][m][bj];
;                         const f32x4 b0 = {__uint_as_float(r.x << 16), __uint_as_float(r.x & 0xffff0000u), __uint_as_float(r.y << 16), __uint_as_float(r.y & 0xffff0000u)};
;                         const f32x4 b1 = {__uint_as_float(r.z << 16), __uint_as_float(r.z & 0xffff0000u), __uint_as_float(r.w << 16), __uint_as_float(r.w & 0xffff0000u)};
;                         tail(b0, b1, acc[ai][bj][m][0], acc[ai][bj][m][1], out + off + bj * HALF, s); }
.Lp6_kdone:
	s_waitcnt lgkmcnt(0)
	s_nop 7
	s_nop 7
	v_and_b32_e32 v254, 63, v185
	v_and_b32_e32 v255, 15, v254
	v_lshrrev_b32_e32 v234, 4, v254
	s_lshl_b32 s40, s37, 6
	v_add_u32_e32 v255, s40, v255
	v_lshlrev_b32_e32 v230, 2, v255
	v_lshlrev_b32_e32 v228, 12, v255
	v_lshlrev_b32_e32 v229, 13, v255
	s_lshl_b32 s41, s38, 6
	v_lshl_add_u32 v228, v234, 4, v228
	v_add_u32_e32 v228, s41, v228
	s_lshl_b32 s41, s38, 7
	v_lshl_add_u32 v229, v234, 5, v229
	v_add_u32_e32 v229, s41, v229
	v_mov_b32_e32 v231, 0x358637bd
	v_xor_b32_e32 v232, 16, v254
	v_lshlrev_b32_e32 v232, 2, v232
	v_xor_b32_e32 v233, 32, v254
	v_lshlrev_b32_e32 v233, 2, v233
	s_lshl_b32 s40, s17, 20
	s_lshl_b32 s41, s18, 9
	s_add_u32 s40, s40, s41
	s_add_u32 s48, s76, 0x6800000
	s_addc_u32 s49, s77, 0
	s_add_u32 s48, s48, s40
	s_addc_u32 s49, s49, 0
	s_lshl_b32 s40, s17, 10
	s_add_u32 s40, s40, 0x10000
	s_add_u32 s50, s76, s40
	s_addc_u32 s51, s77, 0
	v_readlane_b32 s52, v244, 2
	v_readlane_b32 s53, v244, 3
	s_lshl_b32 s40, s17, 21
	s_lshl_b32 s41, s18, 10
	s_add_u32 s40, s40, s41
	s_add_u32 s52, s52, s40
	s_addc_u32 s53, s53, 0
	s_lshl_b32 s40, s17, 6
	s_add_u32 s40, s40, 0x28000
	s_add_u32 s54, s76, s40
	s_addc_u32 s55, s77, 0
	v_add_u32_e32 v234, 0x0, v228
	global_load_dwordx4 v[128:131], v234, s[48:49] offset:0
	global_load_dwordx4 v[132:135], v234, s[48:49] offset:256
	v_add_u32_e32 v234, 0x10000, v228
	global_load_dwordx4 v[136:139], v234, s[48:49] offset:0
	global_load_dwordx4 v[140:143], v234, s[48:49] offset:256
	v_add_u32_e32 v234, 0x20000, v228
	global_load_dwordx4 v[144:147], v234, s[48:49] offset:0
	global_load_dwordx4 v[148:151], v234, s[48:49] offset:256
	v_add_u32_e32 v234, 0x30000, v228
	global_load_dwordx4 v[152:155], v234, s[48:49] offset:0
	global_load_dwordx4 v[156:159], v234, s[48:49] offset:256
	v_add_u32_e32 v234, 0x80000, v228
	global_load_dwordx4 v[160:163], v234, s[48:49] offset:0
	global_load_dwordx4 v[164:167], v234, s[48:49] offset:256
	v_add_u32_e32 v234, 0x90000, v228
	global_load_dwordx4 v[168:171], v234, s[48:49] offset:0
	global_load_dwordx4 v[172:175], v234, s[48:49] offset:256
	v_add_u32_e32 v234, 0xa0000, v228
	global_load_dwordx4 v[176:179], v234, s[48:49] offset:0
	global_load_dwordx4 v[180:183], v234, s[48:49] offset:256
	v_add_u32_e32 v234, 0xb0000, v228
	global_load_dwordx4 v[188:191], v234, s[48:49] offset:0
	global_load_dwordx4 v[192:195], v234, s[48:49] offset:256
	s_waitcnt vmcnt(0)
	v_lshlrev_b32_e32 v254, 16, v128
	v_and_b32_e32 v255, 0xffff0000, v128
	v_add_f32_e32 v0, v0, v254
	v_add_f32_e32 v1, v1, v255
	v_mul_f32_e32 v238, v0, v0
	v_fmac_f32_e32 v238, v1, v1
	v_lshlrev_b32_e32 v254, 16, v129
	v_and_b32_e32 v255, 0xffff0000, v129
	v_add_f32_e32 v2, v2, v254
	v_add_f32_e32 v3, v3, v255
	v_fmac_f32_e32 v238, v2, v2
	v_fmac_f32_e32 v238, v3, v3
	v_lshlrev_b32_e32 v254, 16, v130
	v_and_b32_e32 v255, 0xffff0000, v130
	v_add_f32_e32 v4, v4, v254
	v_add_f32_e32 v5, v5, v255
	v_fmac_f32_e32 v238, v4, v4
	v_fmac_f32_e32 v238, v5, v5
	v_lshlrev_b32_e32 v254, 16, v131
	v_and_b32_e32 v255, 0xffff0000, v131
	v_add_f32_e32 v6, v6, v254
	v_add_f32_e32 v7, v7, v255
	v_fmac_f32_e32 v238, v6, v6
	v_fmac_f32_e32 v238, v7, v7
	v_lshlrev_b32_e32 v254, 16, v132
	v_and_b32_e32 v255, 0xffff0000, v132
	v_add_f32_e32 v32, v32, v254
	v_add_f32_e32 v33, v33, v255
	v_fmac_f32_e32 v238, v32, v32
	v_fmac_f32_e32 v238, v33, v33
	v_lshlrev_b32_e32 v254, 16, v133
	v_and_b32_e32 v255, 0xffff0000, v133
	v_add_f32_e32 v34, v34, v254
	v_add_f32_e32 v35, v35, v255
	v_fmac_f32_e32 v238, v34, v34
	v_fmac_f32_e32 v238, v35, v35
	v_lshlrev_b32_e32 v254, 16, v134
	v_and_b32_e32 v255, 0xffff0000, v134
	v_add_f32_e32 v36, v36, v254
	v_add_f32_e32 v37, v37, v255
	v_fmac_f32_e32 v238, v36, v36
	v_fmac_f32_e32 v238, v37, v37
	v_lshlrev_b32_e32 v254, 16, v135
	v_and_b32_e32 v255, 0xffff0000, v135
	v_add_f32_e32 v38, v38, v254
	v_add_f32_e32 v39, v39, v255
	v_fmac_f32_e32 v238, v38, v38
	v_fmac_f32_e32 v238, v39, v39
	v_lshlrev_b32_e32 v254, 16, v136
	v_and_b32_e32 v255, 0xffff0000, v136
	v_add_f32_e32 v8, v8, v254
	v_add_f32_e32 v9, v9, v255
	v_mul_f32_e32 v239, v8, v8
	v_fmac_f32_e32 v239, v9, v9
	v_lshlrev_b32_e32 v254, 16, v137
	v_and_b32_e32 v255, 0xffff0000, v137
	v_add_f32_e32 v10, v10, v254
	v_add_f32_e32 v11, v11, v255
	v_fmac_f32_e32 v239, v10, v10
	v_fmac_f32_e32 v239, v11, v11
	v_lshlrev_b32_e32 v254, 16, v138
	v_and_b32_e32 v255, 0xffff0000, v138
	v_add_f32_e32 v12, v12, v254
	v_add_f32_e32 v13, v13, v255
	v_fmac_f32_e32 v239, v12, v12
	v_fmac_f32_e32 v239, v13, v13
	v_lshlrev_b32_e32 v254, 16, v139
	v_and_b32_e32 v255, 0xffff0000, v139
	v_add_f32_e32 v14, v14, v254
	v_add_f32_e32 v15, v15, v255
	v_fmac_f32_e32 v239, v14, v14
	v_fmac_f32_e32 v239, v15, v15
	v_lshlrev_b32_e32 v254, 16, v140
	v_and_b32_e32 v255, 0xffff0000, v140
	v_add_f32_e32 v40, v40, v254
	v_add_f32_e32 v41, v41, v255
	v_fmac_f32_e32 v239, v40, v40
	v_fmac_f32_e32 v239, v41, v41
	v_lshlrev_b32_e32 v254, 16, v141
	v_and_b32_e32 v255, 0xffff0000, v141
	v_add_f32_e32 v42, v42, v254
	v_add_f32_e32 v43, v43, v255
	v_fmac_f32_e32 v239, v42, v42
	v_fmac_f32_e32 v239, v43, v43
	v_lshlrev_b32_e32 v254, 16, v142
	v_and_b32_e32 v255, 0xffff0000, v142
	v_add_f32_e32 v44, v44, v254
	v_add_f32_e32 v45, v45, v255
	v_fmac_f32_e32 v239, v44, v44
	v_fmac_f32_e32 v239, v45, v45
	v_lshlrev_b32_e32 v254, 16, v143
	v_and_b32_e32 v255, 0xffff0000, v143
	v_add_f32_e32 v46, v46, v254
	v_add_f32_e32 v47, v47, v255
	v_fmac_f32_e32 v239, v46, v46
	v_fmac_f32_e32 v239, v47, v47
	v_lshlrev_b32_e32 v254, 16, v144
	v_and_b32_e32 v255, 0xffff0000, v144
	v_add_f32_e32 v16, v16, v254
	v_add_f32_e32 v17, v17, v255
	v_mul_f32_e32 v240, v16, v16
;     __device__ __forceinline__ void tail(const f32x4& b0, const f32x4& b1, const f32x4& a0, const f32x4& a1, bf16_t* dst, float& s) const {
;         const f32x4 o0 = b0 + a0, o1 = b1 + a1;
;         s += ((o0[0] * o0[0] + o0[1] * o0[1]) + (o0[2] * o0[2] + o0[3] * o0[3])) + ((o1[0] * o1[0] + o1[1] * o1[1]) + (o1[2] * o1[2] + o1[3] * o1[3]));
;     __device__ __forceinline__ void operator()(const f32x4 (&acc)[2][2][4][2], const Unit& u, int wr, int wc, int fr, int fq) const {
;     ...
;                 for (int m = 0; m < 4; ++m) { const int row = u.pm * BM + ai * HALF + wr * 64 + m * 16 + fr; const size_t off = (size_t)row * ldc + col0; float s = 0.f;
; #pragma unroll
;                     for (int bj = 0; bj < 2; ++bj) { const u32x4 r = raw[ai][m][bj];
;                         const f32x4 b0 = {__uint_as_float(r.x << 16), __uint_as_float(r.x & 0xffff0000u), __uint_as_float(r.y << 16), __uint_as_float(r.y & 0xffff0000u)};
;                         const f32x4 b1 = {__uint_as_float(r.z << 16), __uint_as_float(r.z & 0xffff0000u), __uint_as_float(r.w << 16), __uint_as_float(r.w & 0xffff0000u)};
;                         tail(b0, b1, acc[ai][bj][m][0], acc[ai][bj][m][1], out + off + bj * HALF, s); }
	v_fmac_f32_e32 v240, v17, v17
	v_lshlrev_b32_e32 v254, 16, v145
	v_and_b32_e32 v255, 0xffff0000, v145
	v_add_f32_e32 v18, v18, v254
	v_add_f32_e32 v19, v19, v255
	v_fmac_f32_e32 v240, v18, v18
	v_fmac_f32_e32 v240, v19, v19
	v_lshlrev_b32_e32 v254, 16, v146
	v_and_b32_e32 v255, 0xffff0000, v146
	v_add_f32_e32 v20, v20, v254
	v_add_f32_e32 v21, v21, v255
	v_fmac_f32_e32 v240, v20, v20
	v_fmac_f32_e32 v240, v21, v21
	v_lshlrev_b32_e32 v254, 16, v147
	v_and_b32_e32 v255, 0xffff0000, v147
	v_add_f32_e32 v22, v22, v254
	v_add_f32_e32 v23, v23, v255
	v_fmac_f32_e32 v240, v22, v22
	v_fmac_f32_e32 v240, v23, v23
	v_lshlrev_b32_e32 v254, 16, v148
	v_and_b32_e32 v255, 0xffff0000, v148
	v_add_f32_e32 v48, v48, v254
	v_add_f32_e32 v49, v49, v255
	v_fmac_f32_e32 v240, v48, v48
	v_fmac_f32_e32 v240, v49, v49
	v_lshlrev_b32_e32 v254, 16, v149
	v_and_b32_e32 v255, 0xffff0000, v149
	v_add_f32_e32 v50, v50, v254
	v_add_f32_e32 v51, v51, v255
	v_fmac_f32_e32 v240, v50, v50
	v_fmac_f32_e32 v240, v51, v51
	v_lshlrev_b32_e32 v254, 16, v150
	v_and_b32_e32 v255, 0xffff0000, v150
	v_add_f32_e32 v52, v52, v254
	v_add_f32_e32 v53, v53, v255
	v_fmac_f32_e32 v240, v52, v52
	v_fmac_f32_e32 v240, v53, v53
	v_lshlrev_b32_e32 v254, 16, v151
	v_and_b32_e32 v255, 0xffff0000, v151
	v_add_f32_e32 v54, v54, v254
	v_add_f32_e32 v55, v55, v255
	v_fmac_f32_e32 v240, v54, v54
	v_fmac_f32_e32 v240, v55, v55
	v_lshlrev_b32_e32 v254, 16, v152
	v_and_b32_e32 v255, 0xffff0000, v152
	v_add_f32_e32 v24, v24, v254
	v_add_f32_e32 v25, v25, v255
	v_mul_f32_e32 v241, v24, v24
	v_fmac_f32_e32 v241, v25, v25
	v_lshlrev_b32_e32 v254, 16, v153
	v_and_b32_e32 v255, 0xffff0000, v153
	v_add_f32_e32 v26, v26, v254
	v_add_f32_e32 v27, v27, v255
	v_fmac_f32_e32 v241, v26, v26
	v_fmac_f32_e32 v241, v27, v27
	v_lshlrev_b32_e32 v254, 16, v154
	v_and_b32_e32 v255, 0xffff0000, v154
	v_add_f32_e32 v28, v28, v254
	v_add_f32_e32 v29, v29, v255
	v_fmac_f32_e32 v241, v28, v28
	v_fmac_f32_e32 v241, v29, v29
	v_lshlrev_b32_e32 v254, 16, v155
	v_and_b32_e32 v255, 0xffff0000, v155
	v_add_f32_e32 v30, v30, v254
	v_add_f32_e32 v31, v31, v255
	v_fmac_f32_e32 v241, v30, v30
	v_fmac_f32_e32 v241, v31, v31
	v_lshlrev_b32_e32 v254, 16, v156
	v_and_b32_e32 v255, 0xffff0000, v156
	v_add_f32_e32 v56, v56, v254
	v_add_f32_e32 v57, v57, v255
	v_fmac_f32_e32 v241, v56, v56
	v_fmac_f32_e32 v241, v57, v57
	v_lshlrev_b32_e32 v254, 16, v157
	v_and_b32_e32 v255, 0xffff0000, v157
	v_add_f32_e32 v58, v58, v254
	v_add_f32_e32 v59, v59, v255
	v_fmac_f32_e32 v241, v58, v58
	v_fmac_f32_e32 v241, v59, v59
	v_lshlrev_b32_e32 v254, 16, v158
	v_and_b32_e32 v255, 0xffff0000, v158
	v_add_f32_e32 v60, v60, v254
	v_add_f32_e32 v61, v61, v255
	v_fmac_f32_e32 v241, v60, v60
	v_fmac_f32_e32 v241, v61, v61
	v_lshlrev_b32_e32 v254, 16, v159
	v_and_b32_e32 v255, 0xffff0000, v159
	v_add_f32_e32 v62, v62, v254
	v_add_f32_e32 v63, v63, v255
	v_fmac_f32_e32 v241, v62, v62
	v_fmac_f32_e32 v241, v63, v63
	v_lshlrev_b32_e32 v254, 16, v160
	v_and_b32_e32 v255, 0xffff0000, v160
	v_add_f32_e32 v64, v64, v254
	v_add_f32_e32 v65, v65, v255
	v_mul_f32_e32 v242, v64, v64
	v_fmac_f32_e32 v242, v65, v65
	v_lshlrev_b32_e32 v254, 16, v161
	v_and_b32_e32 v255, 0xffff0000, v161
	v_add_f32_e32 v66, v66, v254
	v_add_f32_e32 v67, v67, v255
	v_fmac_f32_e32 v242, v66, v66
	v_fmac_f32_e32 v242, v67, v67
	v_lshlrev_b32_e32 v254, 16, v162
	v_and_b32_e32 v255, 0xffff0000, v162
	v_add_f32_e32 v68, v68, v254
	v_add_f32_e32 v69, v69, v255
	v_fmac_f32_e32 v242, v68, v68
	v_fmac_f32_e32 v242, v69, v69
	v_lshlrev_b32_e32 v254, 16, v163
	v_and_b32_e32 v255, 0xffff0000, v163
	v_add_f32_e32 v70, v70, v254
	v_add_f32_e32 v71, v71, v255
	v_fmac_f32_e32 v242, v70, v70
	v_fmac_f32_e32 v242, v71, v71
	v_lshlrev_b32_e32 v254, 16, v164
	v_and_b32_e32 v255, 0xffff0000, v164
	v_add_f32_e32 v96, v96, v254
	v_add_f32_e32 v97, v97, v255
	v_fmac_f32_e32 v242, v96, v96
	v_fmac_f32_e32 v242, v97, v97
	v_lshlrev_b32_e32 v254, 16, v165
	v_and_b32_e32 v255, 0xffff0000, v165
	v_add_f32_e32 v98, v98, v254
	v_add_f32_e32 v99, v99, v255
	v_fmac_f32_e32 v242, v98, v98
	v_fmac_f32_e32 v242, v99, v99
	v_lshlrev_b32_e32 v254, 16, v166
	v_and_b32_e32 v255, 0xffff0000, v166
	v_add_f32_e32 v100, v100, v254
	v_add_f32_e32 v101, v101, v255
	v_fmac_f32_e32 v242, v100, v100
	v_fmac_f32_e32 v242, v101, v101
	v_lshlrev_b32_e32 v254, 16, v167
	v_and_b32_e32 v255, 0xffff0000, v167
	v_add_f32_e32 v102, v102, v254
	v_add_f32_e32 v103, v103, v255
	v_fmac_f32_e32 v242, v102, v102
	v_fmac_f32_e32 v242, v103, v103
	v_lshlrev_b32_e32 v254, 16, v168
	v_and_b32_e32 v255, 0xffff0000, v168
	v_add_f32_e32 v72, v72, v254
	v_add_f32_e32 v73, v73, v255
	v_mul_f32_e32 v243, v72, v72
	v_fmac_f32_e32 v243, v73, v73
	v_lshlrev_b32_e32 v254, 16, v169
	v_and_b32_e32 v255, 0xffff0000, v169
	v_add_f32_e32 v74, v74, v254
	v_add_f32_e32 v75, v75, v255
	v_fmac_f32_e32 v243, v74, v74
	v_fmac_f32_e32 v243, v75, v75
	v_lshlrev_b32_e32 v254, 16, v170
	v_and_b32_e32 v255, 0xffff0000, v170
	v_add_f32_e32 v76, v76, v254
	v_add_f32_e32 v77, v77, v255
	v_fmac_f32_e32 v243, v76, v76
	v_fmac_f32_e32 v243, v77, v77
	v_lshlrev_b32_e32 v254, 16, v171
	v_and_b32_e32 v255, 0xffff0000, v171
	v_add_f32_e32 v78, v78, v254
	v_add_f32_e32 v79, v79, v255
	v_fmac_f32_e32 v243, v78, v78
	v_fmac_f32_e32 v243, v79, v79
	v_lshlrev_b32_e32 v254, 16, v172
	v_and_b32_e32 v255, 0xffff0000, v172
	v_add_f32_e32 v104, v104, v254
	v_add_f32_e32 v105, v105, v255
	v_fmac_f32_e32 v243, v104, v104
	v_fmac_f32_e32 v243, v105, v105
	v_lshlrev_b32_e32 v254, 16, v173
	v_and_b32_e32 v255, 0xffff0000, v173
	v_add_f32_e32 v106, v106, v254
	v_add_f32_e32 v107, v107, v255
	v_fmac_f32_e32 v243, v106, v106
;     __device__ __forceinline__ void operator()(const f32x4 (&acc)[2][2][4][2], const Unit& u, int wr, int wc, int fr, int fq) const {
;     ...
;                     for (int bj = 0; bj < 2; ++bj) { const u32x4 r = raw[ai][m][bj];
;                         const f32x4 b0 = {__uint_as_float(r.x << 16), __uint_as_float(r.x & 0xffff0000u), __uint_as_float(r.y << 16), __uint_as_float(r.y & 0xffff0000u)};
;                         const f32x4 b1 = {__uint_as_float(r.z << 16), __uint_as_float(r.z & 0xffff0000u), __uint_as_float(r.w << 16), __uint_as_float(r.w & 0xffff0000u)};
;                         tail(b0, b1, acc[ai][bj][m][0], acc[ai][bj][m][1], out + off + bj * HALF, s); }
;                     s += __shfl_xor(s, 16); s += __shfl_xor(s, 32);
;                     if (fq == 0) atomicAdd(ss + row, s); }
	v_fmac_f32_e32 v243, v107, v107
	v_lshlrev_b32_e32 v254, 16, v174
	v_and_b32_e32 v255, 0xffff0000, v174
	v_add_f32_e32 v108, v108, v254
	v_add_f32_e32 v109, v109, v255
	v_fmac_f32_e32 v243, v108, v108
	v_fmac_f32_e32 v243, v109, v109
	v_lshlrev_b32_e32 v254, 16, v175
	v_and_b32_e32 v255, 0xffff0000, v175
	v_add_f32_e32 v110, v110, v254
	v_add_f32_e32 v111, v111, v255
	v_fmac_f32_e32 v243, v110, v110
	v_fmac_f32_e32 v243, v111, v111
	v_lshlrev_b32_e32 v254, 16, v176
	v_and_b32_e32 v255, 0xffff0000, v176
	v_add_f32_e32 v80, v80, v254
	v_add_f32_e32 v81, v81, v255
	v_mul_f32_e32 v226, v80, v80
	v_fmac_f32_e32 v226, v81, v81
	v_lshlrev_b32_e32 v254, 16, v177
	v_and_b32_e32 v255, 0xffff0000, v177
	v_add_f32_e32 v82, v82, v254
	v_add_f32_e32 v83, v83, v255
	v_fmac_f32_e32 v226, v82, v82
	v_fmac_f32_e32 v226, v83, v83
	v_lshlrev_b32_e32 v254, 16, v178
	v_and_b32_e32 v255, 0xffff0000, v178
	v_add_f32_e32 v84, v84, v254
	v_add_f32_e32 v85, v85, v255
	v_fmac_f32_e32 v226, v84, v84
	v_fmac_f32_e32 v226, v85, v85
	v_lshlrev_b32_e32 v254, 16, v179
	v_and_b32_e32 v255, 0xffff0000, v179
	v_add_f32_e32 v86, v86, v254
	v_add_f32_e32 v87, v87, v255
	v_fmac_f32_e32 v226, v86, v86
	v_fmac_f32_e32 v226, v87, v87
	v_lshlrev_b32_e32 v254, 16, v180
	v_and_b32_e32 v255, 0xffff0000, v180
	v_add_f32_e32 v112, v112, v254
	v_add_f32_e32 v113, v113, v255
	v_fmac_f32_e32 v226, v112, v112
	v_fmac_f32_e32 v226, v113, v113
	v_lshlrev_b32_e32 v254, 16, v181
	v_and_b32_e32 v255, 0xffff0000, v181
	v_add_f32_e32 v114, v114, v254
	v_add_f32_e32 v115, v115, v255
	v_fmac_f32_e32 v226, v114, v114
	v_fmac_f32_e32 v226, v115, v115
	v_lshlrev_b32_e32 v254, 16, v182
	v_and_b32_e32 v255, 0xffff0000, v182
	v_add_f32_e32 v116, v116, v254
	v_add_f32_e32 v117, v117, v255
	v_fmac_f32_e32 v226, v116, v116
	v_fmac_f32_e32 v226, v117, v117
	v_lshlrev_b32_e32 v254, 16, v183
	v_and_b32_e32 v255, 0xffff0000, v183
	v_add_f32_e32 v118, v118, v254
	v_add_f32_e32 v119, v119, v255
	v_fmac_f32_e32 v226, v118, v118
	v_fmac_f32_e32 v226, v119, v119
	v_lshlrev_b32_e32 v254, 16, v188
	v_and_b32_e32 v255, 0xffff0000, v188
	v_add_f32_e32 v88, v88, v254
	v_add_f32_e32 v89, v89, v255
	v_mul_f32_e32 v227, v88, v88
	v_fmac_f32_e32 v227, v89, v89
	v_lshlrev_b32_e32 v254, 16, v189
	v_and_b32_e32 v255, 0xffff0000, v189
	v_add_f32_e32 v90, v90, v254
	v_add_f32_e32 v91, v91, v255
	v_fmac_f32_e32 v227, v90, v90
	v_fmac_f32_e32 v227, v91, v91
	v_lshlrev_b32_e32 v254, 16, v190
	v_and_b32_e32 v255, 0xffff0000, v190
	v_add_f32_e32 v92, v92, v254
	v_add_f32_e32 v93, v93, v255
	v_fmac_f32_e32 v227, v92, v92
	v_fmac_f32_e32 v227, v93, v93
	v_lshlrev_b32_e32 v254, 16, v191
	v_and_b32_e32 v255, 0xffff0000, v191
	v_add_f32_e32 v94, v94, v254
	v_add_f32_e32 v95, v95, v255
	v_fmac_f32_e32 v227, v94, v94
	v_fmac_f32_e32 v227, v95, v95
	v_lshlrev_b32_e32 v254, 16, v192
	v_and_b32_e32 v255, 0xffff0000, v192
	v_add_f32_e32 v120, v120, v254
	v_add_f32_e32 v121, v121, v255
	v_fmac_f32_e32 v227, v120, v120
	v_fmac_f32_e32 v227, v121, v121
	v_lshlrev_b32_e32 v254, 16, v193
	v_and_b32_e32 v255, 0xffff0000, v193
	v_add_f32_e32 v122, v122, v254
	v_add_f32_e32 v123, v123, v255
	v_fmac_f32_e32 v227, v122, v122
	v_fmac_f32_e32 v227, v123, v123
	v_lshlrev_b32_e32 v254, 16, v194
	v_and_b32_e32 v255, 0xffff0000, v194
	v_add_f32_e32 v124, v124, v254
	v_add_f32_e32 v125, v125, v255
	v_fmac_f32_e32 v227, v124, v124
	v_fmac_f32_e32 v227, v125, v125
	v_lshlrev_b32_e32 v254, 16, v195
	v_and_b32_e32 v255, 0xffff0000, v195
	v_add_f32_e32 v126, v126, v254
	v_add_f32_e32 v127, v127, v255
	v_fmac_f32_e32 v227, v126, v126
	v_fmac_f32_e32 v227, v127, v127
	v_readlane_b32 s44, v244, 0
	v_readlane_b32 s45, v244, 1
	v_and_b32_e32 v254, 63, v185
	v_lshrrev_b32_e32 v254, 4, v254
	v_lshlrev_b32_e32 v254, 5, v254
	s_lshl_b32 s40, s38, 7
	s_lshl_b32 s41, s18, 10
	s_add_u32 s40, s40, s41
	v_add_u32_e32 v254, s40, v254
	global_load_dwordx4 v[160:163], v254, s[44:45] offset:0
	global_load_dwordx4 v[164:167], v254, s[44:45] offset:16
	global_load_dwordx4 v[168:171], v254, s[44:45] offset:512
	global_load_dwordx4 v[172:175], v254, s[44:45] offset:528
	ds_bpermute_b32 v128, v232, v238
	ds_bpermute_b32 v132, v232, v239
	ds_bpermute_b32 v136, v232, v240
	ds_bpermute_b32 v140, v232, v241
	ds_bpermute_b32 v144, v232, v242
	ds_bpermute_b32 v148, v232, v243
	ds_bpermute_b32 v152, v232, v226
	ds_bpermute_b32 v156, v232, v227
	s_waitcnt lgkmcnt(0)
	v_add_f32_e32 v238, v238, v128
	v_add_f32_e32 v239, v239, v132
	v_add_f32_e32 v240, v240, v136
	v_add_f32_e32 v241, v241, v140
	v_add_f32_e32 v242, v242, v144
	v_add_f32_e32 v243, v243, v148
	v_add_f32_e32 v226, v226, v152
	v_add_f32_e32 v227, v227, v156
	ds_bpermute_b32 v128, v233, v238
	ds_bpermute_b32 v132, v233, v239
	ds_bpermute_b32 v136, v233, v240
	ds_bpermute_b32 v140, v233, v241
	ds_bpermute_b32 v144, v233, v242
	ds_bpermute_b32 v148, v233, v243
	ds_bpermute_b32 v152, v233, v226
	ds_bpermute_b32 v156, v233, v227
	s_waitcnt lgkmcnt(0)
	v_add_f32_e32 v238, v238, v128
	v_add_f32_e32 v239, v239, v132
	v_add_f32_e32 v240, v240, v136
	v_add_f32_e32 v241, v241, v140
	v_add_f32_e32 v242, v242, v144
	v_add_f32_e32 v243, v243, v148
	v_add_f32_e32 v226, v226, v152
	v_add_f32_e32 v227, v227, v156
	s_mov_b64 exec, 0xffff
	global_atomic_add_f32 v230, v238, s[50:51] offset:0
	global_atomic_add_f32 v230, v239, s[50:51] offset:64
	global_atomic_add_f32 v230, v240, s[50:51] offset:128
	global_atomic_add_f32 v230, v241, s[50:51] offset:192
	global_atomic_add_f32 v230, v242, s[50:51] offset:512
	global_atomic_add_f32 v230, v243, s[50:51] offset:576
	global_atomic_add_f32 v230, v226, s[50:51] offset:640
	global_atomic_add_f32 v230, v227, s[50:51] offset:704
	s_mov_b64 exec, -1
	s_waitcnt vmcnt(0)
	s_barrier
	s_cmp_lg_u32 s36, 0
	s_cbranch_scc1 .Lp6_fin_arr
	s_mov_b64 exec, 1
	v_mov_b32_e32 v237, 0
	v_mov_b32_e32 v236, 1
	global_atomic_add v237, v236, s[54:55]
	s_mov_b64 exec, -1
.Lp6_fin_arr:
	s_cmp_lg_u32 s36, 0
	s_cbranch_scc1 .Lp6_fin_wait
	s_mov_b64 exec, 1
	v_mov_b32_e32 v237, 0
	s_mov_b32 s42, 0
